# stacked: v_mov_b64 accumulator zeroing, attention next-tile LDS publish before PV, DPP row sums in phase 2, stagger step 5
# speedup vs baseline: 1.0070x; 1.0070x over previous
; template <class Epi>
; DEVI void gemm_phase(LAS unsigned char* lds, const Gemm g, const StaticOrder& S, const Epi& E, const int tid) {
;     ...
;         const bool has_next = S.next(ui + 1, nxt);
;         const char* nA = has_next ? (const char*)g.A + (size_t)nxt.pm * tstepA : cA; const char* nB = has_next ? (const char*)g.Bt + (size_t)nxt.pn * tstepB : cB;
;     ...
; #pragma unroll
;         for (int a = 0; a < 2; ++a)
; #pragma unroll
;             for (int b = 0; b < 2; ++b)
; #pragma unroll
;                 for (int m = 0; m < 4; ++m)
; #pragma unroll
;                     for (int n = 0; n < 2; ++n) acc[a][b][m][n] = (f4){0.f, 0.f, 0.f, 0.f};
;         cur = nxt; cA = nA; cB = nB; ++ui;
.LBB0_145:
	v_mov_b64_e32 v[0:1], 0x39c
	s_ashr_i32 s23, s22, 31
	v_cmp_lt_i64_e32 vcc, s[6:7], v[0:1]
	s_lshl_b64 s[6:7], s[22:23], 19
	s_add_u32 s24, s49, s6
	s_addc_u32 s25, s50, s7
	s_and_b64 s[6:7], vcc, exec
	s_cselect_b32 s1, s25, s35
	s_cselect_b32 s23, s24, s34
	s_ashr_i32 s21, s20, 31
	s_lshl_b64 s[6:7], s[20:21], 19
	s_add_u32 s26, s51, s6
	s_addc_u32 s27, s52, s7
	s_and_b64 s[6:7], vcc, exec
	s_cselect_b32 s21, s27, s31
	s_cselect_b32 s29, s26, s30
	s_add_u32 s6, s34, 0x40080
	s_addc_u32 s7, s35, 0
	s_add_u32 s36, s30, 0x100
	v_mov_b32_e32 v0, 0
	s_addc_u32 s37, s31, 0
	s_mov_b32 s38, -2
	v_mov_b32_e32 v1, v0
	v_mov_b64_e32 v[2:3], v[0:1]
	v_mov_b64_e32 v[4:5], v[0:1]
	v_mov_b64_e32 v[6:7], v[0:1]
	v_mov_b64_e32 v[8:9], v[0:1]
	v_mov_b64_e32 v[10:11], v[0:1]
	v_mov_b64_e32 v[12:13], v[0:1]
	v_mov_b64_e32 v[14:15], v[0:1]
	v_mov_b64_e32 v[16:17], v[0:1]
	v_mov_b64_e32 v[18:19], v[0:1]
	v_mov_b64_e32 v[20:21], v[0:1]
	v_mov_b64_e32 v[22:23], v[0:1]
	v_mov_b64_e32 v[24:25], v[0:1]
	v_mov_b64_e32 v[26:27], v[0:1]
	v_mov_b64_e32 v[28:29], v[0:1]
	v_mov_b64_e32 v[30:31], v[0:1]
	v_mov_b64_e32 v[82:83], v[0:1]
	v_mov_b64_e32 v[84:85], v[0:1]
	v_mov_b64_e32 v[86:87], v[0:1]
	v_mov_b64_e32 v[88:89], v[0:1]
	v_mov_b64_e32 v[90:91], v[0:1]
	v_mov_b64_e32 v[92:93], v[0:1]
	v_mov_b64_e32 v[94:95], v[0:1]
	v_mov_b64_e32 v[96:97], v[0:1]
	v_mov_b64_e32 v[98:99], v[0:1]
	v_mov_b64_e32 v[100:101], v[0:1]
	v_mov_b64_e32 v[102:103], v[0:1]
	v_mov_b64_e32 v[104:105], v[0:1]
	v_mov_b64_e32 v[106:107], v[0:1]
	v_mov_b64_e32 v[108:109], v[0:1]
	v_mov_b64_e32 v[110:111], v[0:1]
	v_mov_b64_e32 v[112:113], v[0:1]
	v_mov_b64_e32 v[32:33], v[0:1]
	v_mov_b64_e32 v[34:35], v[0:1]
	v_mov_b64_e32 v[36:37], v[0:1]
	v_mov_b64_e32 v[38:39], v[0:1]
	v_mov_b64_e32 v[58:59], v[0:1]
	v_mov_b64_e32 v[60:61], v[0:1]
	v_mov_b64_e32 v[62:63], v[0:1]
	v_mov_b64_e32 v[64:65], v[0:1]
	v_mov_b64_e32 v[66:67], v[0:1]
	v_mov_b64_e32 v[68:69], v[0:1]
	v_mov_b64_e32 v[70:71], v[0:1]
	v_mov_b64_e32 v[72:73], v[0:1]
	v_mov_b64_e32 v[74:75], v[0:1]
	v_mov_b64_e32 v[76:77], v[0:1]
	v_mov_b64_e32 v[78:79], v[0:1]
	v_mov_b64_e32 v[80:81], v[0:1]
	v_mov_b64_e32 v[114:115], v[0:1]
	v_mov_b64_e32 v[116:117], v[0:1]
	v_mov_b64_e32 v[118:119], v[0:1]
	v_mov_b64_e32 v[120:121], v[0:1]
	v_mov_b64_e32 v[138:139], v[0:1]
	v_mov_b64_e32 v[140:141], v[0:1]
	v_mov_b64_e32 v[142:143], v[0:1]
	v_mov_b64_e32 v[144:145], v[0:1]
	v_mov_b64_e32 v[146:147], v[0:1]
	v_mov_b64_e32 v[148:149], v[0:1]
	v_mov_b64_e32 v[150:151], v[0:1]
	v_mov_b64_e32 v[152:153], v[0:1]
	v_mov_b64_e32 v[154:155], v[0:1]
	v_mov_b64_e32 v[156:157], v[0:1]
	v_mov_b64_e32 v[158:159], v[0:1]
	v_mov_b64_e32 v[160:161], v[0:1]

; DEVI float shx(float v, int o, int lane) { return __builtin_bit_cast(float, __builtin_amdgcn_ds_bpermute((lane ^ o) << 2, __builtin_bit_cast(int, v))); }
; __global__ void __launch_bounds__(512, 2) trunk_fwd(Params p) {
;     ...
;                 for (int o = 1; o < 64; o <<= 1) { ssq += shx(ssq, o, lane); sskv += shx(sskv, o, lane); }
;                 { const float rr = rsqrtf(ssq * (1.f / 384.f) + 1e-6f);
.LBB0_299:
	s_waitcnt vmcnt(4)
	v_cvt_f32_f16_sdwa v25, v14 dst_sel:DWORD dst_unused:UNUSED_PAD src0_sel:WORD_1
	v_cvt_f32_f16_e32 v24, v14
	v_cvt_f32_f16_sdwa v27, v15 dst_sel:DWORD dst_unused:UNUSED_PAD src0_sel:WORD_1
	v_cvt_f32_f16_e32 v26, v15
	v_cvt_f32_f16_e32 v32, v17
	v_cvt_f32_f16_e32 v34, v16
	v_cvt_f32_f16_sdwa v19, v18 dst_sel:DWORD dst_unused:UNUSED_PAD src0_sel:WORD_1
	v_cvt_f32_f16_e32 v18, v18
	v_cvt_f32_f16_sdwa v33, v17 dst_sel:DWORD dst_unused:UNUSED_PAD src0_sel:WORD_1
	v_cvt_f32_f16_sdwa v35, v16 dst_sel:DWORD dst_unused:UNUSED_PAD src0_sel:WORD_1
	v_mov_b32_e32 v16, v32
	v_mov_b32_e32 v17, v34
	v_pk_mul_f32 v[28:29], v[24:25], v[24:25]
	v_pk_mul_f32 v[72:73], v[18:19], v[18:19]
	v_pk_mul_f32 v[16:17], v[16:17], v[16:17]
	v_mov_b32_e32 v82, v33
	v_mov_b32_e32 v83, v35
	v_pk_mul_f32 v[30:31], v[26:27], v[26:27]
	v_pk_fma_f32 v[16:17], v[82:83], v[82:83], v[16:17]
	v_mov_b32_e32 v82, v28
	v_mov_b32_e32 v83, v73
	v_pk_mov_b32 v[28:29], v[28:29], v[72:73] op_sel:[1,0]
	v_mov_b32_e32 v72, v30
	v_pk_add_f32 v[28:29], v[82:83], v[28:29]
	v_mov_b32_e32 v73, v16
	v_pk_add_f32 v[28:29], v[28:29], v[72:73]
	v_mov_b32_e32 v16, v31
	v_pk_add_f32 v[16:17], v[28:29], v[16:17]
	v_add_co_u32_e32 v12, vcc, 0xa8d1000, v12
	v_lshl_add_u64 v[30:31], s[14:15], 0, v[56:57]
	s_nop 0
	v_addc_co_u32_e32 v13, vcc, 0, v13, vcc
	v_add_f32_dpp v134, v16, v16 row_shr:1 row_mask:0xf bank_mask:0xf bound_ctrl:0
	v_add_f32_dpp v135, v17, v17 row_shr:1 row_mask:0xf bank_mask:0xf bound_ctrl:0
	v_add_f32_dpp v134, v16, v134 row_shr:2 row_mask:0xf bank_mask:0xf bound_ctrl:0
	v_add_f32_dpp v135, v17, v135 row_shr:2 row_mask:0xf bank_mask:0xf bound_ctrl:0
	v_add_f32_dpp v134, v16, v134 row_shr:3 row_mask:0xf bank_mask:0xf bound_ctrl:0
	v_add_f32_dpp v135, v17, v135 row_shr:3 row_mask:0xf bank_mask:0xf bound_ctrl:0
	s_nop 1
	v_add_f32_dpp v134, v134, v134 row_shr:4 row_mask:0xf bank_mask:0xe
	v_add_f32_dpp v135, v135, v135 row_shr:4 row_mask:0xf bank_mask:0xe
	s_nop 1
	v_add_f32_dpp v134, v134, v134 row_shr:8 row_mask:0xf bank_mask:0xc
	v_add_f32_dpp v135, v135, v135 row_shr:8 row_mask:0xf bank_mask:0xc
	s_nop 1
	v_add_f32_dpp v134, v134, v134 row_bcast:15 row_mask:0xa bank_mask:0xf
	v_add_f32_dpp v135, v135, v135 row_bcast:15 row_mask:0xa bank_mask:0xf
	s_nop 1
	v_add_f32_dpp v134, v134, v134 row_bcast:31 row_mask:0xc bank_mask:0xf
	v_add_f32_dpp v135, v135, v135 row_bcast:31 row_mask:0xc bank_mask:0xf
	s_nop 1
	v_readlane_b32 s100, v134, 63
	v_readlane_b32 s101, v135, 63
	s_mov_b32 s8, 0x11c51000
	v_add_co_u32_e64 v30, s[8:9], s8, v30
	s_mov_b64 s[42:43], -1
	s_nop 1
	v_addc_co_u32_e64 v31, s[8:9], 0, v31, s[8:9]
	v_lshl_add_u64 v[72:73], s[14:15], 0, v[58:59]
	s_nop 1
	v_mov_b32_e32 v16, s100
	v_mov_b32_e32 v17, s101
	v_mov_b32_e32 v28, 0x358637bd
	v_pk_fma_f32 v[28:29], v[16:17], s[84:85], v[28:29] op_sel_hi:[1,1,0]
	s_nop 0
	v_mul_f32_e32 v16, 0x4b800000, v29
	v_cmp_gt_f32_e32 vcc, s69, v29
	v_cmp_gt_f32_e64 s[8:9], s69, v28
	s_nop 0
	v_cndmask_b32_e32 v16, v29, v16, vcc
	v_rsq_f32_e32 v29, v16
	v_mul_f32_e32 v12, 0x45800000, v29
	v_cndmask_b32_e32 v12, v29, v12, vcc
	v_pk_mul_f32 v[32:33], v[12:13], v[32:33] op_sel_hi:[0,1]
	v_pk_mul_f32 v[14:15], v[32:33], v[100:101]
	s_and_b64 vcc, exec, s[6:7]
	v_cvt_pk_f16_f32 v13, v14, v15
	global_store_dword v[30:31], v13, off
	v_pk_mul_f32 v[18:19], v[12:13], v[18:19] op_sel_hi:[0,1]
	v_pk_mul_f32 v[14:15], v[18:19], v[102:103]
	s_nop 0
	v_cvt_pk_f16_f32 v13, v14, v15
	global_store_dword v[30:31], v13, off offset:256
	v_pk_mul_f32 v[12:13], v[12:13], v[34:35] op_sel_hi:[0,1]
	v_mul_f32_e32 v18, 0x4b800000, v28
	v_cndmask_b32_e64 v18, v28, v18, s[8:9]
	v_rsq_f32_e32 v18, v18
	v_pk_mul_f32 v[12:13], v[12:13], v[104:105]
	s_nop 0
	v_cvt_pk_f16_f32 v12, v12, v13
	global_store_dword v[30:31], v12, off offset:512
	v_mul_f32_e32 v19, 0x45800000, v18
	v_cndmask_b32_e64 v18, v18, v19, s[8:9]
	v_pk_mul_f32 v[26:27], v[26:27], v[18:19] op_sel_hi:[1,0]
	v_pk_mul_f32 v[18:19], v[24:25], v[18:19] op_sel_hi:[1,0]
	s_waitcnt vmcnt(3)
	v_pk_mul_f32 v[14:15], v[26:27], v[108:109]
	v_pk_mul_f32 v[12:13], v[18:19], v[106:107]
	v_cvt_pk_f16_f32 v19, v14, v15
	v_cvt_pk_f16_f32 v18, v12, v13
	s_cbranch_vccnz .LBB0_302
	v_lshl_add_u64 v[24:25], s[12:13], 0, v[64:65]
	global_store_dwordx4 v[24:25], v[12:15], off nt
	v_add_co_u32_e32 v24, vcc, 0x13511000, v72
	s_nop 1
	v_addc_co_u32_e32 v25, vcc, 0, v73, vcc
	global_store_dwordx2 v[24:25], v[18:19], off
	s_cbranch_execz .LBB0_303

; #define LAS __attribute__((address_space(3)))
; DEVI float shx(float v, int o, int lane) { return __builtin_bit_cast(float, __builtin_amdgcn_ds_bpermute((lane ^ o) << 2, __builtin_bit_cast(int, v))); }
; template <int NKS, int NCT, int NQS, int KSTR>
; DEVI void attn_qk(LAS unsigned char* kbase, const h8 (&qf)[NQS][NKS], f4 (&o)[NQS][NCT], float (&mrow)[NQS], float (&lrow)[NQS], h8 (&pf)[NQS][2], const int nkt, const int lane) {
;     ...
;     for (int kt = 0; kt < 4; ++kt) if (kt < nkt) {
; #pragma unroll
;         for (int qs = 0; qs < NQS; ++qs) s[qs][kt] = (f4){0.f, 0.f, 0.f, 0.f};
; #pragma unroll
;         for (int ks = 0; ks < NKS; ++ks) { const h8 kf = *(const LAS h8*)(kbase + (kt * 16 + fr) * KSTR + ks * 64 + g * 16);
; #pragma unroll
;             for (int qs = 0; qs < NQS; ++qs) s[qs][kt] = __builtin_amdgcn_mfma_f32_16x16x32_f16(kf, qf[qs][ks], s[qs][kt], 0, 0, 0); } }
;     __builtin_amdgcn_sched_barrier(0);
; #pragma unroll
;     for (int qs = 0; qs < NQS; ++qs) {
;         float mx = -1e30f;
; #pragma unroll
;         for (int kt = 0; kt < 4; ++kt)
; #pragma unroll
;             for (int e = 0; e < 4; ++e) mx = fmaxf(mx, s[qs][kt][e]);
;         mx = fmaxf(mx, shx(mx, 16, lane)); mx = fmaxf(mx, shx(mx, 32, lane));
;         const float mnew = fmaxf(mrow[qs], mx), alpha = __builtin_amdgcn_exp2f(mrow[qs] - mnew); mrow[qs] = mnew;
;         float ps = 0.f;
; #pragma unroll
;         for (int kt = 0; kt < 4; ++kt)
; #pragma unroll
;             for (int e = 0; e < 4; ++e) { const float p = __builtin_amdgcn_exp2f(s[qs][kt][e] - mnew); s[qs][kt][e] = p; ps += p; }
.LBB0_886:
	s_and_b32 s8, s30, 1
	s_mul_i32 s9, s8, 0x3800
	v_add_u32_e32 v83, s9, v104
	v_add_u32_e32 v96, v83, v105
	v_add_u32_e32 v83, v83, v106
	s_mulk_i32 s8, 0x2800
	ds_read_b128 v[150:153], v96
	ds_read_b128 v[154:157], v96 offset:64
	ds_read_b128 v[158:161], v96 offset:128
	ds_read_b128 v[162:165], v96 offset:3584
	ds_read_b128 v[168:171], v96 offset:3648
	ds_read_b128 v[172:175], v96 offset:3712
	ds_read_b128 v[176:179], v96 offset:7168
	ds_read_b128 v[180:183], v96 offset:7232
	ds_read_b128 v[184:187], v96 offset:7296
	ds_read_b128 v[188:191], v83
	ds_read_b128 v[192:195], v83 offset:64
	ds_read_b128 v[196:199], v83 offset:128
	s_waitcnt lgkmcnt(11)
	v_mfma_f32_16x16x32_f16 v[88:91], v[150:153], v[0:3], 0
	v_mfma_f32_16x16x32_f16 v[108:111], v[150:153], v[12:15], 0
	s_waitcnt lgkmcnt(10)
	v_mfma_f32_16x16x32_f16 v[88:91], v[154:157], v[4:7], v[88:91]
	v_mfma_f32_16x16x32_f16 v[108:111], v[154:157], v[16:19], v[108:111]
	s_waitcnt lgkmcnt(9)
	v_mfma_f32_16x16x32_f16 v[88:91], v[158:161], v[8:11], v[88:91]
	v_mfma_f32_16x16x32_f16 v[108:111], v[158:161], v[20:23], v[108:111]
	s_waitcnt lgkmcnt(8)
	v_mfma_f32_16x16x32_f16 v[92:95], v[162:165], v[0:3], 0
	v_mfma_f32_16x16x32_f16 v[112:115], v[162:165], v[12:15], 0
	s_waitcnt lgkmcnt(7)
	v_mfma_f32_16x16x32_f16 v[92:95], v[168:171], v[4:7], v[92:95]
	v_mfma_f32_16x16x32_f16 v[112:115], v[168:171], v[16:19], v[112:115]
	s_waitcnt lgkmcnt(6)
	v_mfma_f32_16x16x32_f16 v[92:95], v[172:175], v[8:11], v[92:95]
	v_mfma_f32_16x16x32_f16 v[112:115], v[172:175], v[20:23], v[112:115]
	s_waitcnt lgkmcnt(5)
	v_mfma_f32_16x16x32_f16 v[116:119], v[176:179], v[0:3], 0
	v_mfma_f32_16x16x32_f16 v[120:123], v[176:179], v[12:15], 0
	s_waitcnt lgkmcnt(4)
	v_mfma_f32_16x16x32_f16 v[116:119], v[180:183], v[4:7], v[116:119]
	v_mfma_f32_16x16x32_f16 v[120:123], v[180:183], v[16:19], v[120:123]
	s_waitcnt lgkmcnt(3)
	v_mfma_f32_16x16x32_f16 v[116:119], v[184:187], v[8:11], v[116:119]
	v_mfma_f32_16x16x32_f16 v[120:123], v[184:187], v[20:23], v[120:123]
	s_waitcnt lgkmcnt(2)
	v_mfma_f32_16x16x32_f16 v[124:127], v[188:191], v[0:3], 0
	v_mfma_f32_16x16x32_f16 v[128:131], v[188:191], v[12:15], 0
	s_waitcnt lgkmcnt(1)
	v_mfma_f32_16x16x32_f16 v[124:127], v[192:195], v[4:7], v[124:127]
	v_mfma_f32_16x16x32_f16 v[128:131], v[192:195], v[16:19], v[128:131]
	s_waitcnt lgkmcnt(0)
	v_mfma_f32_16x16x32_f16 v[124:127], v[196:199], v[8:11], v[124:127]
	v_mfma_f32_16x16x32_f16 v[128:131], v[196:199], v[20:23], v[128:131]
	s_nop 3
	s_mov_b32 s9, 0xf149f2ca
	v_max3_f32 v83, v88, s9, v89
	v_max3_f32 v83, v83, v90, v91
	v_max3_f32 v83, v83, v92, v93
	v_max3_f32 v83, v83, v94, v95
	v_max3_f32 v83, v83, v116, v117
	v_max3_f32 v83, v83, v118, v119
	v_max3_f32 v83, v83, v124, v125
	v_max3_f32 v83, v83, v126, v127
	ds_bpermute_b32 v84, v100, v83
	s_waitcnt lgkmcnt(0)
	v_max_f32_e32 v84, v84, v84
	v_max_f32_e32 v83, v83, v84
	ds_bpermute_b32 v84, v99, v83
	s_waitcnt lgkmcnt(0)
	v_max3_f32 v148, v82, v83, v84
	v_sub_f32_e32 v83, v82, v148
	v_sub_f32_e32 v82, v88, v148
	v_exp_f32_e32 v132, v82
	v_sub_f32_e32 v82, v93, v148
	v_exp_f32_e32 v142, v82
	v_sub_f32_e32 v82, v94, v148
	v_exp_f32_e32 v144, v82
	v_sub_f32_e32 v82, v95, v148
	v_exp_f32_e32 v146, v82
	v_sub_f32_e32 v82, v116, v148
	v_exp_f32_e32 v116, v83
	v_max3_f32 v83, v108, s9, v109
	v_sub_f32_e32 v85, v90, v148
	v_max3_f32 v83, v83, v110, v111
	v_sub_f32_e32 v86, v91, v148
	v_exp_f32_e32 v136, v85
	v_sub_f32_e32 v85, v118, v148
	v_max3_f32 v83, v83, v112, v113
	v_exp_f32_e32 v138, v86
	v_exp_f32_e32 v86, v85
	v_sub_f32_e32 v85, v119, v148
	v_max3_f32 v83, v83, v114, v115
	v_exp_f32_e32 v88, v85
	v_sub_f32_e32 v85, v124, v148
	v_max3_f32 v83, v83, v120, v121
	v_exp_f32_e32 v90, v85
	v_sub_f32_e32 v85, v125, v148
	v_max3_f32 v83, v83, v122, v123
	v_sub_f32_e32 v87, v92, v148
	v_exp_f32_e32 v92, v85
	v_sub_f32_e32 v85, v126, v148
	v_max3_f32 v83, v83, v128, v129
	v_exp_f32_e32 v94, v85
	v_sub_f32_e32 v85, v127, v148
	v_max3_f32 v83, v83, v130, v131
	v_exp_f32_e32 v96, v85
	ds_bpermute_b32 v85, v100, v83
	v_sub_f32_e32 v84, v89, v148
	v_exp_f32_e32 v134, v84
	v_exp_f32_e32 v140, v87
	v_exp_f32_e32 v82, v82
	s_waitcnt lgkmcnt(0)
	v_max_f32_e32 v85, v85, v85
	v_max_f32_e32 v83, v83, v85
	ds_bpermute_b32 v85, v99, v83
	v_sub_f32_e32 v84, v117, v148
	v_exp_f32_e32 v84, v84
	v_pk_mul_f32 v[56:57], v[56:57], v[116:117] op_sel_hi:[1,0]
	v_pk_mul_f32 v[54:55], v[54:55], v[116:117] op_sel_hi:[1,0]
	s_waitcnt lgkmcnt(0)
; #define LAS __attribute__((address_space(3)))
; DEVI h4 trrd(LAS unsigned char* p) { s4v r = __builtin_amdgcn_ds_read_tr16_b64_v4i16((LAS s4v*)p); return __builtin_bit_cast(h4, r); }
; DEVI h8 cat44(h4 a, h4 b) { return __builtin_shufflevector(a, b, 0, 1, 2, 3, 4, 5, 6, 7); }
; template <int NKS, int NCT, int NQS, int KSTR>
; DEVI void attn_qk(LAS unsigned char* kbase, const h8 (&qf)[NQS][NKS], f4 (&o)[NQS][NCT], float (&mrow)[NQS], float (&lrow)[NQS], h8 (&pf)[NQS][2], const int nkt, const int lane) {
;     ...
;             for (int e = 0; e < 4; ++e) { const float p = __builtin_amdgcn_exp2f(s[qs][kt][e] - mnew); s[qs][kt][e] = p; ps += p; }
;         lrow[qs] = lrow[qs] * alpha + ps;
; #pragma unroll
;         for (int ct = 0; ct < NCT; ++ct) o[qs][ct] *= alpha;
; #pragma unroll
;         for (int k2 = 0; k2 < 2; ++k2) pf[qs][k2] = pack8(s[qs][2 * k2], s[qs][2 * k2 + 1]);
;     }
;     __builtin_amdgcn_sched_barrier(0);
; }
; template <int NCT, int NQS, int VSTR>
; DEVI void attn_pv(LAS unsigned char* vbase, f4 (&o)[NQS][NCT], const h8 (&pf)[NQS][2], const int nkt, const int lane) {
;     const int fr = lane & 15, g = lane >> 4, q_ = fr >> 2, p_ = fr & 3;
; #pragma unroll
;     for (int k2 = 0; k2 < 2; ++k2) if (2 * k2 < nkt) {
; #pragma unroll
;         for (int ct = 0; ct < NCT; ++ct) {
;             const h4 lo = trrd(vbase + (32 * k2 + 4 * g + q_) * VSTR + (16 * ct + 4 * p_) * 2);
;             const h4 hi = trrd(vbase + (32 * k2 + 16 + 4 * g + q_) * VSTR + (16 * ct + 4 * p_) * 2);
;             const h8 vf = cat44(lo, hi);
; #pragma unroll
;             for (int qs = 0; qs < NQS; ++qs) o[qs][ct] = __builtin_amdgcn_mfma_f32_16x16x32_f16(vf, pf[qs][k2], o[qs][ct], 0, 0, 0); } }
; __global__ void __launch_bounds__(512, 2) trunk_fwd(Params p) {
;     ...
;                         if (t + 1 < ntb) { *(LAS h8*)(lds + no * KBUF + lk0) = pk0; if (tix < 256) *(LAS h8*)(lds + no * KBUF + lk1) = pk1; *(LAS h8*)(lds + no * VBUF + lv) = pv; }
	v_add_u32_e32 v250, s8, v107
	ds_read_b64_tr_b16 v[200:201], v250 offset:28672
	ds_read_b64_tr_b16 v[202:203], v250 offset:31232
	ds_read_b64_tr_b16 v[204:205], v250 offset:28704
	ds_read_b64_tr_b16 v[206:207], v250 offset:31264
	ds_read_b64_tr_b16 v[212:213], v250 offset:28736
	ds_read_b64_tr_b16 v[214:215], v250 offset:31296
	ds_read_b64_tr_b16 v[216:217], v250 offset:28768
	ds_read_b64_tr_b16 v[218:219], v250 offset:31328
	ds_read_b64_tr_b16 v[232:233], v250 offset:33792
	ds_read_b64_tr_b16 v[234:235], v250 offset:36352
	ds_read_b64_tr_b16 v[236:237], v250 offset:33824
	ds_read_b64_tr_b16 v[238:239], v250 offset:36384
	ds_read_b64_tr_b16 v[240:241], v250 offset:33856
	ds_read_b64_tr_b16 v[242:243], v250 offset:36416
	ds_read_b64_tr_b16 v[246:247], v250 offset:33888
	ds_read_b64_tr_b16 v[248:249], v250 offset:36448
	v_max3_f32 v124, v48, v83, v85
	v_sub_f32_e32 v83, v108, v124
	v_exp_f32_e32 v133, v83
	v_sub_f32_e32 v83, v109, v124
	v_exp_f32_e32 v135, v83
	v_sub_f32_e32 v83, v110, v124
	v_exp_f32_e32 v137, v83
	v_sub_f32_e32 v83, v111, v124
	v_exp_f32_e32 v139, v83
	v_sub_f32_e32 v83, v112, v124
	v_exp_f32_e32 v141, v83
	v_sub_f32_e32 v83, v113, v124
	v_pk_add_f32 v[108:109], v[132:133], 0 op_sel_hi:[1,0]
	v_exp_f32_e32 v143, v83
	v_pk_add_f32 v[108:109], v[134:135], v[108:109]
	v_sub_f32_e32 v83, v114, v124
	v_pk_add_f32 v[108:109], v[136:137], v[108:109]
	v_exp_f32_e32 v145, v83
	v_sub_f32_e32 v83, v115, v124
	v_pk_add_f32 v[108:109], v[138:139], v[108:109]
	v_exp_f32_e32 v147, v83
	v_sub_f32_e32 v83, v120, v124
	v_pk_add_f32 v[108:109], v[140:141], v[108:109]
	v_exp_f32_e32 v83, v83
	v_sub_f32_e32 v85, v121, v124
	v_pk_add_f32 v[108:109], v[142:143], v[108:109]
	v_exp_f32_e32 v85, v85
	v_sub_f32_e32 v87, v122, v124
	v_exp_f32_e32 v87, v87
	v_sub_f32_e32 v89, v123, v124
	v_pk_add_f32 v[108:109], v[144:145], v[108:109]
	v_exp_f32_e32 v89, v89
	v_sub_f32_e32 v91, v128, v124
	v_pk_add_f32 v[108:109], v[146:147], v[108:109]
	v_exp_f32_e32 v91, v91
	v_sub_f32_e32 v93, v129, v124
	v_pk_add_f32 v[108:109], v[82:83], v[108:109]
	v_exp_f32_e32 v93, v93
	v_sub_f32_e32 v95, v130, v124
	v_pk_add_f32 v[108:109], v[84:85], v[108:109]
	v_sub_f32_e32 v48, v48, v124
	v_exp_f32_e32 v95, v95
	v_sub_f32_e32 v97, v131, v124
	v_pk_add_f32 v[108:109], v[86:87], v[108:109]
	v_pk_mul_f32 v[60:61], v[60:61], v[116:117] op_sel_hi:[1,0]
	v_pk_mul_f32 v[58:59], v[58:59], v[116:117] op_sel_hi:[1,0]
	v_pk_mul_f32 v[64:65], v[64:65], v[116:117] op_sel_hi:[1,0]
	v_pk_mul_f32 v[62:63], v[62:63], v[116:117] op_sel_hi:[1,0]
	v_pk_mul_f32 v[68:69], v[68:69], v[116:117] op_sel_hi:[1,0]
	v_pk_mul_f32 v[66:67], v[66:67], v[116:117] op_sel_hi:[1,0]
	v_exp_f32_e32 v97, v97
	v_exp_f32_e32 v117, v48
	v_pk_add_f32 v[108:109], v[88:89], v[108:109]
	v_mov_b32_e32 v48, v117
	v_pk_add_f32 v[108:109], v[90:91], v[108:109]
	v_pk_mul_f32 v[30:31], v[30:31], v[48:49] op_sel_hi:[1,0]
	v_pk_add_f32 v[108:109], v[92:93], v[108:109]
	v_pk_mul_f32 v[28:29], v[28:29], v[48:49] op_sel_hi:[1,0]
	v_pk_add_f32 v[108:109], v[94:95], v[108:109]
	v_pk_mul_f32 v[34:35], v[34:35], v[48:49] op_sel_hi:[1,0]
	v_pk_add_f32 v[108:109], v[96:97], v[108:109]
	v_pk_mul_f32 v[32:33], v[32:33], v[48:49] op_sel_hi:[1,0]
	v_pk_fma_f32 v[74:75], v[74:75], v[116:117], v[108:109]
	v_pk_mul_f32 v[42:43], v[42:43], v[48:49] op_sel_hi:[1,0]
	v_pk_mul_f32 v[40:41], v[40:41], v[48:49] op_sel_hi:[1,0]
	v_pk_mul_f32 v[46:47], v[48:49], v[46:47] op_sel_hi:[0,1]
	v_pk_mul_f32 v[44:45], v[48:49], v[44:45] op_sel_hi:[0,1]
	s_andn2_b64 vcc, exec, s[0:1]
	s_cbranch_vccnz .Lpa_nostore
	s_and_b32 s100, s29, 1
	s_mul_i32 s101, s100, 0x3800
	s_add_i32 s101, s101, 16
	v_add_u32_e32 v251, s101, v101
	v_add_u32_e32 v252, s101, v102
	s_mulk_i32 s100, 0x2800
	v_add_u32_e32 v253, s100, v103
	s_waitcnt vmcnt(1)
	ds_write_b128 v251, v[24:27]
	s_and_saveexec_b64 s[100:101], s[6:7]
	ds_write_b128 v252, v[36:39]
	s_or_b64 exec, exec, s[100:101]
	s_waitcnt vmcnt(0)
	ds_write_b128 v253, v[50:53] offset:28672
.Lpa_nostore:
	v_cvt_pk_f16_f32 v115, v144, v146
	v_cvt_pk_f16_f32 v114, v140, v142
	v_cvt_pk_f16_f32 v113, v136, v138
	v_cvt_pk_f16_f32 v112, v132, v134
	v_cvt_pk_f16_f32 v119, v145, v147
	v_cvt_pk_f16_f32 v118, v141, v143
	v_cvt_pk_f16_f32 v117, v137, v139
	v_cvt_pk_f16_f32 v116, v133, v135
	v_cvt_pk_f16_f32 v111, v94, v96
	v_cvt_pk_f16_f32 v110, v90, v92
	v_cvt_pk_f16_f32 v109, v86, v88
	v_cvt_pk_f16_f32 v108, v82, v84
	v_cvt_pk_f16_f32 v95, v95, v97
	v_cvt_pk_f16_f32 v94, v91, v93
	v_cvt_pk_f16_f32 v93, v87, v89
	v_cvt_pk_f16_f32 v92, v83, v85
	s_waitcnt lgkmcnt(14)
	v_mfma_f32_16x16x32_f16 v[54:57], v[200:203], v[112:115], v[54:57]
	v_mfma_f32_16x16x32_f16 v[28:31], v[200:203], v[116:119], v[28:31]
	s_waitcnt lgkmcnt(12)
	v_mfma_f32_16x16x32_f16 v[58:61], v[204:207], v[112:115], v[58:61]
	v_mfma_f32_16x16x32_f16 v[32:35], v[204:207], v[116:119], v[32:35]
	s_waitcnt lgkmcnt(10)
	v_mfma_f32_16x16x32_f16 v[62:65], v[212:215], v[112:115], v[62:65]
	v_mfma_f32_16x16x32_f16 v[40:43], v[212:215], v[116:119], v[40:43]
	s_waitcnt lgkmcnt(8)
	v_mfma_f32_16x16x32_f16 v[66:69], v[216:219], v[112:115], v[66:69]
	v_mfma_f32_16x16x32_f16 v[44:47], v[216:219], v[116:119], v[44:47]
	s_waitcnt lgkmcnt(6)
	v_mfma_f32_16x16x32_f16 v[54:57], v[232:235], v[108:111], v[54:57]
	v_mfma_f32_16x16x32_f16 v[28:31], v[232:235], v[92:95], v[28:31]
	s_waitcnt lgkmcnt(4)
	v_mfma_f32_16x16x32_f16 v[58:61], v[236:239], v[108:111], v[58:61]
	v_mfma_f32_16x16x32_f16 v[32:35], v[236:239], v[92:95], v[32:35]
	s_waitcnt lgkmcnt(2)
	v_mfma_f32_16x16x32_f16 v[62:65], v[240:243], v[108:111], v[62:65]
	v_mfma_f32_16x16x32_f16 v[40:43], v[240:243], v[92:95], v[40:43]
	s_waitcnt lgkmcnt(0)
	v_mfma_f32_16x16x32_f16 v[66:69], v[246:249], v[108:111], v[66:69]
	v_mfma_f32_16x16x32_f16 v[44:47], v[246:249], v[92:95], v[44:47]
	v_mov_b32_e32 v82, v148
	v_mov_b32_e32 v48, v124
	s_branch .LBB0_890

; #define PG8_STAGE(bufoff, gbase, voff) do { _Pragma("unroll") for (int _i = 0; _i < 2; ++_i) \
;         __builtin_amdgcn_global_load_lds((const unsigned*)((const char*)(gbase) + (voff)[_i]), (LAS unsigned*)(lds + (bufoff) + ldsw + _i * 8192), 16, 0, 0); } while (0)
; #define PG8_WAIT_V(n) asm volatile("s_waitcnt vmcnt(" #n ")" ::: "memory")
; #define PG8_BAR __builtin_amdgcn_s_barrier()
; template <class Epi>
; DEVI void gemm_phase(LAS unsigned char* lds, const Gemm g, const StaticOrder& S, const Epi& E, const int tid) {
;     ...
;     f4 acc[2][2][4][2];
; #pragma unroll
;     for (int a = 0; a < 2; ++a)
; #pragma unroll
;         for (int b = 0; b < 2; ++b)
; #pragma unroll
;             for (int m = 0; m < 4; ++m)
; #pragma unroll
;                 for (int n = 0; n < 2; ++n) acc[a][b][m][n] = (f4){0.f, 0.f, 0.f, 0.f};
;     h8 At[4][2], B0[2][2], B1[2][2];
;     const char* cA = (const char*)g.A + (size_t)cur.pm * tstepA; const char* cB = (const char*)g.Bt + (size_t)cur.pn * tstepB;
;     PG8_STAGE(PG8_SB(0, 0), cB, voffB); PG8_STAGE(PG8_SA(0, 0), cA, voffA); PG8_STAGE(PG8_SB(0, 1), cB + hstepB, voffB); PG8_STAGE(PG8_SA(0, 1), cA + hstepA, voffA);
;     if (wr == 1) PG8_BAR;
;     PG8_WAIT_V(4); PG8_BAR;
;     PG8_STAGE(PG8_SB(1, 0), cB + kstep, voffB); PG8_STAGE(PG8_SA(1, 0), cA + kstep, voffA); PG8_STAGE(PG8_SB(1, 1), cB + hstepB + kstep, voffB);
;     PG8_WAIT_V(6); PG8_BAR;
.LBB0_937:
	v_and_b32_e32 v14, 48, v225
	v_lshlrev_b32_e32 v21, 2, v230
	s_lshl_b32 s30, s30, 5
	s_lshl_b32 s83, s31, 6
	s_lshl_b32 s31, s31, 13
	v_lshl_or_b32 v14, v230, 6, v14
	v_and_b32_e32 v21, 32, v21
	s_and_b32 s30, s30, 0x60
	v_bitop3_b32 v22, v14, s31, v21 bitop3:0xde
	s_lshl_b32 s31, s30, 7
	s_add_i32 m0, s88, 0x18000
	v_lshl_add_u64 v[12:13], v[12:13], 0, s[78:79]
	s_lshl_b64 s[0:1], s[56:57], 18
	v_bitop3_b32 v14, s31, v14, v21 bitop3:0xf6
	s_waitcnt vmcnt(4)
	s_barrier
	global_load_lds_dwordx4 v[12:13], off
	v_lshl_add_u64 v[10:11], v[10:11], 0, s[78:79]
	s_add_i32 m0, s88, 0x1a000
	s_add_i32 s31, s88, 0x8000
	s_add_i32 s42, s88, 0xa000
	global_load_lds_dwordx4 v[10:11], off
	v_lshl_add_u64 v[8:9], v[8:9], 0, s[78:79]
	s_mov_b32 m0, s31
	s_add_u32 s62, s60, 0x40080
	global_load_lds_dwordx4 v[8:9], off
	v_lshl_add_u64 v[6:7], v[6:7], 0, s[78:79]
	s_mov_b32 m0, s42
	s_addc_u32 s63, s61, 0
	global_load_lds_dwordx4 v[6:7], off
	s_add_i32 m0, s88, 0x1c000
	v_lshl_add_u64 v[6:7], s[62:63], 0, v[48:49]
	global_load_lds_dwordx4 v[6:7], off
	v_lshl_add_u64 v[6:7], s[62:63], 0, v[4:5]
	s_add_i32 m0, s88, 0x1e000
	v_lshlrev_b32_e32 v8, 14, v18
	global_load_lds_dwordx4 v[6:7], off
	v_lshlrev_b32_e32 v6, 14, v15
	s_ashr_i32 s55, s54, 31
	v_and_b32_e32 v6, 0xffff8000, v6
	v_and_b32_e32 v8, 0xffff8000, v8
	s_lshl_b64 s[62:63], s[54:55], 19
	v_lshl_add_u32 v6, v16, 11, v6
	v_and_b32_e32 v7, 1, v15
	v_lshl_add_u32 v8, v19, 11, v8
	v_and_b32_e32 v9, 1, v18
	s_waitcnt vmcnt(6)
	v_lshl_or_b32 v6, v7, 6, v6
	s_add_u32 s62, s14, s62
	v_lshl_or_b32 v8, v9, 6, v8
	v_lshl_add_u32 v6, v17, 1, v6
	v_mov_b32_e32 v7, v49
	s_addc_u32 s63, s15, s63
	v_lshl_add_u32 v8, v20, 1, v8
	v_mov_b32_e32 v9, v49
	s_waitcnt vmcnt(0)
	v_mov_b32_e32 v50, 0
	v_lshl_add_u64 v[6:7], s[62:63], 0, v[6:7]
	v_lshl_add_u64 v[8:9], s[62:63], 0, v[8:9]
	s_mov_b32 s43, -2
	s_mov_b64 s[62:63], 0x257d1080
	v_add_u32_e32 v10, 16, v22
	v_mov_b32_e32 v51, v50
	v_mov_b64_e32 v[52:53], v[50:51]
	v_mov_b64_e32 v[54:55], v[50:51]
	v_mov_b64_e32 v[56:57], v[50:51]
	v_mov_b64_e32 v[66:67], v[50:51]
	v_mov_b64_e32 v[68:69], v[50:51]
	v_mov_b64_e32 v[70:71], v[50:51]
	v_mov_b64_e32 v[72:73], v[50:51]
	v_mov_b64_e32 v[82:83], v[50:51]
	v_mov_b64_e32 v[84:85], v[50:51]
	v_mov_b64_e32 v[86:87], v[50:51]
	v_mov_b64_e32 v[88:89], v[50:51]
	v_mov_b64_e32 v[98:99], v[50:51]
	v_mov_b64_e32 v[100:101], v[50:51]
	v_mov_b64_e32 v[102:103], v[50:51]
	v_mov_b64_e32 v[104:105], v[50:51]
	v_mov_b64_e32 v[58:59], v[50:51]
	v_mov_b64_e32 v[60:61], v[50:51]
	v_mov_b64_e32 v[62:63], v[50:51]
	v_mov_b64_e32 v[64:65], v[50:51]
	v_mov_b64_e32 v[74:75], v[50:51]
	v_mov_b64_e32 v[76:77], v[50:51]
	v_mov_b64_e32 v[78:79], v[50:51]
	v_mov_b64_e32 v[80:81], v[50:51]
	v_mov_b64_e32 v[90:91], v[50:51]
	v_mov_b64_e32 v[92:93], v[50:51]
	v_mov_b64_e32 v[94:95], v[50:51]
	v_mov_b64_e32 v[96:97], v[50:51]
	v_mov_b64_e32 v[106:107], v[50:51]
	v_mov_b64_e32 v[108:109], v[50:51]
	v_mov_b64_e32 v[110:111], v[50:51]
	v_mov_b64_e32 v[112:113], v[50:51]
	v_mov_b64_e32 v[114:115], v[50:51]
	v_mov_b64_e32 v[116:117], v[50:51]
	v_mov_b64_e32 v[118:119], v[50:51]
	v_mov_b64_e32 v[120:121], v[50:51]
	v_mov_b64_e32 v[160:161], v[50:51]
	v_mov_b64_e32 v[162:163], v[50:51]
	v_mov_b64_e32 v[164:165], v[50:51]
	v_mov_b64_e32 v[166:167], v[50:51]
	v_mov_b64_e32 v[176:177], v[50:51]
	v_mov_b64_e32 v[178:179], v[50:51]
	v_mov_b64_e32 v[180:181], v[50:51]
	v_mov_b64_e32 v[182:183], v[50:51]
	v_mov_b64_e32 v[192:193], v[50:51]
	v_mov_b64_e32 v[194:195], v[50:51]
	v_mov_b64_e32 v[196:197], v[50:51]
	v_mov_b64_e32 v[198:199], v[50:51]
	v_mov_b64_e32 v[152:153], v[50:51]
	v_mov_b64_e32 v[154:155], v[50:51]
	v_mov_b64_e32 v[156:157], v[50:51]
	v_mov_b64_e32 v[158:159], v[50:51]
	v_mov_b64_e32 v[168:169], v[50:51]
	v_mov_b64_e32 v[170:171], v[50:51]
	v_mov_b64_e32 v[172:173], v[50:51]
	v_mov_b64_e32 v[174:175], v[50:51]
	v_mov_b64_e32 v[184:185], v[50:51]
	v_mov_b64_e32 v[186:187], v[50:51]
	v_mov_b64_e32 v[188:189], v[50:51]
	v_mov_b64_e32 v[190:191], v[50:51]
	v_mov_b64_e32 v[200:201], v[50:51]
	v_mov_b64_e32 v[202:203], v[50:51]
	v_mov_b64_e32 v[204:205], v[50:51]
	v_mov_b64_e32 v[206:207], v[50:51]
	s_barrier

; template <class Epi>
; DEVI void gemm_phase(LAS unsigned char* lds, const Gemm g, const StaticOrder& S, const Epi& E, const int tid) {
;     ...
;         const bool has_next = S.next(ui + 1, nxt);
;         const char* nA = has_next ? (const char*)g.A + (size_t)nxt.pm * tstepA : cA; const char* nB = has_next ? (const char*)g.Bt + (size_t)nxt.pn * tstepB : cB;
;     ...
; #pragma unroll
;         for (int a = 0; a < 2; ++a)
; #pragma unroll
;             for (int b = 0; b < 2; ++b)
; #pragma unroll
;                 for (int m = 0; m < 4; ++m)
; #pragma unroll
;                     for (int n = 0; n < 2; ++n) acc[a][b][m][n] = (f4){0.f, 0.f, 0.f, 0.f};
;         cur = nxt; cA = nA; cB = nB; ++ui;
.LBB0_1106:
	s_ashr_i32 s23, s22, 31
	v_cmp_lt_i64_e32 vcc, s[6:7], v[210:211]
	s_lshl_b64 s[6:7], s[22:23], 19
	s_add_u32 s24, s37, s6
	s_addc_u32 s25, s38, s7
	s_and_b64 s[6:7], vcc, exec
	s_cselect_b32 s1, s25, s35
	s_cselect_b32 s23, s24, s34
	s_ashr_i32 s21, s20, 31
	s_lshl_b64 s[6:7], s[20:21], 19
	s_add_u32 s26, s39, s6
	s_addc_u32 s27, s40, s7
	s_and_b64 s[6:7], vcc, exec
	s_cselect_b32 s21, s27, s31
	s_cselect_b32 s51, s26, s30
	s_add_u32 s6, s34, 0x40080
	s_addc_u32 s7, s35, 0
	s_add_u32 s52, s30, 0x100
	v_mov_b32_e32 v50, 0
	s_addc_u32 s53, s31, 0
	s_mov_b32 s54, -2
	v_mov_b32_e32 v51, v50
	v_mov_b64_e32 v[52:53], v[50:51]
	v_mov_b64_e32 v[54:55], v[50:51]
	v_mov_b64_e32 v[56:57], v[50:51]
	v_mov_b64_e32 v[66:67], v[50:51]
	v_mov_b64_e32 v[68:69], v[50:51]
	v_mov_b64_e32 v[70:71], v[50:51]
	v_mov_b64_e32 v[72:73], v[50:51]
	v_mov_b64_e32 v[82:83], v[50:51]
	v_mov_b64_e32 v[84:85], v[50:51]
	v_mov_b64_e32 v[86:87], v[50:51]
	v_mov_b64_e32 v[88:89], v[50:51]
	v_mov_b64_e32 v[98:99], v[50:51]
	v_mov_b64_e32 v[100:101], v[50:51]
	v_mov_b64_e32 v[102:103], v[50:51]
	v_mov_b64_e32 v[104:105], v[50:51]
	v_mov_b64_e32 v[58:59], v[50:51]
	v_mov_b64_e32 v[60:61], v[50:51]
	v_mov_b64_e32 v[62:63], v[50:51]
	v_mov_b64_e32 v[64:65], v[50:51]
	v_mov_b64_e32 v[74:75], v[50:51]
	v_mov_b64_e32 v[76:77], v[50:51]
	v_mov_b64_e32 v[78:79], v[50:51]
	v_mov_b64_e32 v[80:81], v[50:51]
	v_mov_b64_e32 v[90:91], v[50:51]
	v_mov_b64_e32 v[92:93], v[50:51]
	v_mov_b64_e32 v[94:95], v[50:51]
	v_mov_b64_e32 v[96:97], v[50:51]
	v_mov_b64_e32 v[106:107], v[50:51]
	v_mov_b64_e32 v[108:109], v[50:51]
	v_mov_b64_e32 v[110:111], v[50:51]
	v_mov_b64_e32 v[112:113], v[50:51]
	v_mov_b64_e32 v[114:115], v[50:51]
	v_mov_b64_e32 v[116:117], v[50:51]
	v_mov_b64_e32 v[118:119], v[50:51]
	v_mov_b64_e32 v[120:121], v[50:51]
	v_mov_b64_e32 v[160:161], v[50:51]
	v_mov_b64_e32 v[162:163], v[50:51]
	v_mov_b64_e32 v[164:165], v[50:51]
	v_mov_b64_e32 v[166:167], v[50:51]
	v_mov_b64_e32 v[176:177], v[50:51]
	v_mov_b64_e32 v[178:179], v[50:51]
	v_mov_b64_e32 v[180:181], v[50:51]
	v_mov_b64_e32 v[182:183], v[50:51]
	v_mov_b64_e32 v[192:193], v[50:51]
	v_mov_b64_e32 v[194:195], v[50:51]
	v_mov_b64_e32 v[196:197], v[50:51]
	v_mov_b64_e32 v[198:199], v[50:51]
	v_mov_b64_e32 v[148:149], v[50:51]
	v_mov_b64_e32 v[150:151], v[50:51]
	v_mov_b64_e32 v[156:157], v[50:51]
	v_mov_b64_e32 v[158:159], v[50:51]
	v_mov_b64_e32 v[168:169], v[50:51]
	v_mov_b64_e32 v[170:171], v[50:51]
	v_mov_b64_e32 v[172:173], v[50:51]
	v_mov_b64_e32 v[174:175], v[50:51]
	v_mov_b64_e32 v[184:185], v[50:51]
	v_mov_b64_e32 v[186:187], v[50:51]
	v_mov_b64_e32 v[188:189], v[50:51]
	v_mov_b64_e32 v[190:191], v[50:51]
	v_mov_b64_e32 v[200:201], v[50:51]
	v_mov_b64_e32 v[202:203], v[50:51]
	v_mov_b64_e32 v[204:205], v[50:51]
	v_mov_b64_e32 v[206:207], v[50:51]

; template <class Epi>
; DEVI void gemm_phase(LAS unsigned char* lds, const Gemm g, const StaticOrder& S, const Epi& E, const int tid) {
;     ...
;         const bool has_next = S.next(ui + 1, nxt);
;         const char* nA = has_next ? (const char*)g.A + (size_t)nxt.pm * tstepA : cA; const char* nB = has_next ? (const char*)g.Bt + (size_t)nxt.pn * tstepB : cB;
;     ...
; #pragma unroll
;         for (int a = 0; a < 2; ++a)
; #pragma unroll
;             for (int b = 0; b < 2; ++b)
; #pragma unroll
;                 for (int m = 0; m < 4; ++m)
; #pragma unroll
;                     for (int n = 0; n < 2; ++n) acc[a][b][m][n] = (f4){0.f, 0.f, 0.f, 0.f};
;         cur = nxt; cA = nA; cB = nB; ++ui;
.LBB0_1210:
	v_mov_b64_e32 v[0:1], 0xb00
	s_ashr_i32 s9, s8, 31
	v_cmp_lt_i64_e32 vcc, s[10:11], v[0:1]
	s_lshl_b64 s[10:11], s[8:9], 19
	s_add_u32 s10, s23, s10
	s_addc_u32 s11, s24, s11
	s_and_b64 s[12:13], vcc, exec
	s_cselect_b32 s9, s11, s15
	s_cselect_b32 s42, s10, s14
	s_ashr_i32 s7, s6, 31
	s_lshl_b64 s[12:13], s[6:7], 19
	s_add_u32 s12, s25, s12
	s_addc_u32 s13, s26, s13
	s_and_b64 s[18:19], vcc, exec
	s_cselect_b32 s7, s13, s17
	s_cselect_b32 s43, s12, s16
	s_add_u32 s14, s14, 0x40080
	s_addc_u32 s15, s15, 0
	s_add_u32 s44, s16, 0x100
	v_mov_b32_e32 v0, 0
	s_addc_u32 s45, s17, 0
	s_mov_b32 s46, -2
	v_mov_b32_e32 v1, v0
	v_mov_b64_e32 v[2:3], v[0:1]
	v_mov_b64_e32 v[4:5], v[0:1]
	v_mov_b64_e32 v[6:7], v[0:1]
	v_mov_b64_e32 v[8:9], v[0:1]
	v_mov_b64_e32 v[10:11], v[0:1]
	v_mov_b64_e32 v[12:13], v[0:1]
	v_mov_b64_e32 v[14:15], v[0:1]
	v_mov_b64_e32 v[24:25], v[0:1]
	v_mov_b64_e32 v[26:27], v[0:1]
	v_mov_b64_e32 v[28:29], v[0:1]
	v_mov_b64_e32 v[30:31], v[0:1]
	v_mov_b64_e32 v[40:41], v[0:1]
	v_mov_b64_e32 v[42:43], v[0:1]
	v_mov_b64_e32 v[44:45], v[0:1]
	v_mov_b64_e32 v[46:47], v[0:1]
	v_mov_b64_e32 v[16:17], v[0:1]
	v_mov_b64_e32 v[18:19], v[0:1]
	v_mov_b64_e32 v[20:21], v[0:1]
	v_mov_b64_e32 v[22:23], v[0:1]
	v_mov_b64_e32 v[32:33], v[0:1]
	v_mov_b64_e32 v[34:35], v[0:1]
	v_mov_b64_e32 v[36:37], v[0:1]
	v_mov_b64_e32 v[38:39], v[0:1]
	v_mov_b64_e32 v[50:51], v[0:1]
	v_mov_b64_e32 v[52:53], v[0:1]
	v_mov_b64_e32 v[54:55], v[0:1]
	v_mov_b64_e32 v[56:57], v[0:1]
	v_mov_b64_e32 v[58:59], v[0:1]
	v_mov_b64_e32 v[60:61], v[0:1]
	v_mov_b64_e32 v[62:63], v[0:1]
	v_mov_b64_e32 v[64:65], v[0:1]
	v_mov_b64_e32 v[66:67], v[0:1]
	v_mov_b64_e32 v[68:69], v[0:1]
	v_mov_b64_e32 v[70:71], v[0:1]
	v_mov_b64_e32 v[72:73], v[0:1]
	v_mov_b64_e32 v[74:75], v[0:1]
	v_mov_b64_e32 v[76:77], v[0:1]
	v_mov_b64_e32 v[78:79], v[0:1]
	v_mov_b64_e32 v[80:81], v[0:1]
	v_mov_b64_e32 v[90:91], v[0:1]
	v_mov_b64_e32 v[92:93], v[0:1]
	v_mov_b64_e32 v[94:95], v[0:1]
	v_mov_b64_e32 v[96:97], v[0:1]
	v_mov_b64_e32 v[106:107], v[0:1]
	v_mov_b64_e32 v[108:109], v[0:1]
	v_mov_b64_e32 v[110:111], v[0:1]
	v_mov_b64_e32 v[112:113], v[0:1]
	v_mov_b64_e32 v[82:83], v[0:1]
	v_mov_b64_e32 v[84:85], v[0:1]
	v_mov_b64_e32 v[86:87], v[0:1]
	v_mov_b64_e32 v[88:89], v[0:1]
	v_mov_b64_e32 v[98:99], v[0:1]
	v_mov_b64_e32 v[100:101], v[0:1]
	v_mov_b64_e32 v[102:103], v[0:1]
	v_mov_b64_e32 v[104:105], v[0:1]
	v_mov_b64_e32 v[114:115], v[0:1]
	v_mov_b64_e32 v[116:117], v[0:1]
	v_mov_b64_e32 v[118:119], v[0:1]
	v_mov_b64_e32 v[120:121], v[0:1]
	v_mov_b64_e32 v[122:123], v[0:1]
	v_mov_b64_e32 v[124:125], v[0:1]
	v_mov_b64_e32 v[126:127], v[0:1]
	v_mov_b64_e32 v[128:129], v[0:1]

; #define PG8_STAGE(bufoff, gbase, voff) do { _Pragma("unroll") for (int _i = 0; _i < 2; ++_i) \
;         __builtin_amdgcn_global_load_lds((const unsigned*)((const char*)(gbase) + (voff)[_i]), (LAS unsigned*)(lds + (bufoff) + ldsw + _i * 8192), 16, 0, 0); } while (0)
; #define PG8_WAIT_V(n) asm volatile("s_waitcnt vmcnt(" #n ")" ::: "memory")
; #define PG8_BAR __builtin_amdgcn_s_barrier()
; template <class Epi>
; DEVI void gemm_phase(LAS unsigned char* lds, const Gemm g, const StaticOrder& S, const Epi& E, const int tid) {
;     ...
;     f4 acc[2][2][4][2];
; #pragma unroll
;     for (int a = 0; a < 2; ++a)
; #pragma unroll
;         for (int b = 0; b < 2; ++b)
; #pragma unroll
;             for (int m = 0; m < 4; ++m)
; #pragma unroll
;                 for (int n = 0; n < 2; ++n) acc[a][b][m][n] = (f4){0.f, 0.f, 0.f, 0.f};
;     h8 At[4][2], B0[2][2], B1[2][2];
;     const char* cA = (const char*)g.A + (size_t)cur.pm * tstepA; const char* cB = (const char*)g.Bt + (size_t)cur.pn * tstepB;
;     PG8_STAGE(PG8_SB(0, 0), cB, voffB); PG8_STAGE(PG8_SA(0, 0), cA, voffA); PG8_STAGE(PG8_SB(0, 1), cB + hstepB, voffB); PG8_STAGE(PG8_SA(0, 1), cA + hstepA, voffA);
;     if (wr == 1) PG8_BAR;
;     PG8_WAIT_V(4); PG8_BAR;
;     PG8_STAGE(PG8_SB(1, 0), cB + kstep, voffB); PG8_STAGE(PG8_SA(1, 0), cA + kstep, voffA); PG8_STAGE(PG8_SB(1, 1), cB + hstepB + kstep, voffB);
;     PG8_WAIT_V(6); PG8_BAR;
.LBB0_1285:
	v_and_b32_e32 v16, 48, v192
	v_lshlrev_b32_e32 v17, 6, v192
	v_and_or_b32 v16, v17, s95, v16
	v_lshlrev_b32_e32 v17, 2, v192
	s_lshl_b32 s12, s20, 13
	v_and_b32_e32 v17, 32, v17
	v_bitop3_b32 v18, v16, s12, v17 bitop3:0xde
	s_lshl_b32 s12, s19, 5
	s_and_b32 s23, s12, 0x60
	s_add_i32 m0, s25, 0x18000
	v_lshl_add_u64 v[6:7], v[6:7], 0, s[78:79]
	s_lshl_b32 s26, s20, 6
	s_lshl_b32 s12, s23, 7
	s_waitcnt vmcnt(4)
	s_barrier
	global_load_lds_dwordx4 v[6:7], off
	v_lshl_add_u64 v[4:5], v[4:5], 0, s[78:79]
	s_add_i32 m0, s25, 0x1a000
	s_add_i32 s30, s25, 0x8000
	s_add_i32 s31, s25, 0xa000
	v_bitop3_b32 v84, s12, v16, v17 bitop3:0xf6
	global_load_lds_dwordx4 v[4:5], off
	v_lshl_add_u64 v[2:3], v[2:3], 0, s[78:79]
	s_mov_b32 m0, s30
	s_add_u32 s12, s16, 0xb0080
	global_load_lds_dwordx4 v[2:3], off
	v_lshl_add_u64 v[0:1], v[0:1], 0, s[78:79]
	s_mov_b32 m0, s31
	s_addc_u32 s13, s17, 0
	global_load_lds_dwordx4 v[0:1], off
	s_add_i32 m0, s25, 0x1c000
	v_lshl_add_u64 v[0:1], s[12:13], 0, v[48:49]
	global_load_lds_dwordx4 v[0:1], off
	v_lshl_add_u64 v[0:1], s[12:13], 0, v[78:79]
	s_add_i32 m0, s25, 0x1e000
	s_mov_b32 s20, 0xb000
	global_load_lds_dwordx4 v[0:1], off
	v_lshrrev_b32_e32 v1, 1, v8
	v_mul_lo_u32 v0, v10, s51
	s_mul_hi_i32 s19, s18, 0x160000
	s_mul_i32 s18, s18, 0x160000
	v_mad_u64_u32 v[0:1], s[12:13], v1, s20, v[0:1]
	v_or_b32_e32 v0, v0, v9
	s_add_u32 s12, s8, s18
	v_add_lshl_u32 v0, v0, v11, 1
	v_mov_b32_e32 v1, v49
	s_addc_u32 s13, s9, s19
	v_lshl_add_u64 v[80:81], s[12:13], 0, v[0:1]
	v_lshrrev_b32_e32 v1, 1, v12
	v_mul_lo_u32 v0, v14, s51
	v_mad_u64_u32 v[0:1], s[18:19], v1, s20, v[0:1]
	v_or_b32_e32 v0, v0, v13
	s_waitcnt vmcnt(6)
	v_add_lshl_u32 v0, v0, v15, 1
	v_mov_b32_e32 v1, v49
	v_lshl_add_u64 v[82:83], s[12:13], 0, v[0:1]
	v_mov_b32_e32 v0, 0
	s_mov_b32 s34, -2
	s_mov_b64 s[12:13], 0x58251080
	v_add_u32_e32 v85, 16, v18
	v_mov_b32_e32 v1, v0
	v_mov_b64_e32 v[2:3], v[0:1]
	v_mov_b64_e32 v[4:5], v[0:1]
	v_mov_b64_e32 v[6:7], v[0:1]
	v_mov_b64_e32 v[16:17], v[0:1]
	v_mov_b64_e32 v[18:19], v[0:1]
	v_mov_b64_e32 v[20:21], v[0:1]
	v_mov_b64_e32 v[22:23], v[0:1]
	v_mov_b64_e32 v[32:33], v[0:1]
	v_mov_b64_e32 v[34:35], v[0:1]
	v_mov_b64_e32 v[36:37], v[0:1]
	v_mov_b64_e32 v[38:39], v[0:1]
	v_mov_b64_e32 v[50:51], v[0:1]
	v_mov_b64_e32 v[52:53], v[0:1]
	v_mov_b64_e32 v[54:55], v[0:1]
	v_mov_b64_e32 v[56:57], v[0:1]
	v_mov_b64_e32 v[8:9], v[0:1]
	v_mov_b64_e32 v[10:11], v[0:1]
	v_mov_b64_e32 v[12:13], v[0:1]
	v_mov_b64_e32 v[14:15], v[0:1]
	v_mov_b64_e32 v[24:25], v[0:1]
	v_mov_b64_e32 v[26:27], v[0:1]
	v_mov_b64_e32 v[28:29], v[0:1]
	v_mov_b64_e32 v[30:31], v[0:1]
	v_mov_b64_e32 v[40:41], v[0:1]
	v_mov_b64_e32 v[42:43], v[0:1]
	v_mov_b64_e32 v[44:45], v[0:1]
	v_mov_b64_e32 v[46:47], v[0:1]
	v_mov_b64_e32 v[58:59], v[0:1]
	v_mov_b64_e32 v[60:61], v[0:1]
	v_mov_b64_e32 v[62:63], v[0:1]
	v_mov_b64_e32 v[64:65], v[0:1]
	v_mov_b64_e32 v[66:67], v[0:1]
	v_mov_b64_e32 v[68:69], v[0:1]
	v_mov_b64_e32 v[70:71], v[0:1]
	v_mov_b64_e32 v[72:73], v[0:1]
	v_mov_b64_e32 v[114:115], v[0:1]
	v_mov_b64_e32 v[116:117], v[0:1]
	v_mov_b64_e32 v[118:119], v[0:1]
	v_mov_b64_e32 v[120:121], v[0:1]
	v_mov_b64_e32 v[130:131], v[0:1]
	v_mov_b64_e32 v[132:133], v[0:1]
	v_mov_b64_e32 v[134:135], v[0:1]
	v_mov_b64_e32 v[136:137], v[0:1]
	v_mov_b64_e32 v[146:147], v[0:1]
	v_mov_b64_e32 v[148:149], v[0:1]
	v_mov_b64_e32 v[150:151], v[0:1]
	v_mov_b64_e32 v[152:153], v[0:1]
	v_mov_b64_e32 v[98:99], v[0:1]
	v_mov_b64_e32 v[100:101], v[0:1]
	v_mov_b64_e32 v[110:111], v[0:1]
	v_mov_b64_e32 v[112:113], v[0:1]
	v_mov_b64_e32 v[122:123], v[0:1]
	v_mov_b64_e32 v[124:125], v[0:1]
	v_mov_b64_e32 v[126:127], v[0:1]
	v_mov_b64_e32 v[128:129], v[0:1]
	v_mov_b64_e32 v[138:139], v[0:1]
	v_mov_b64_e32 v[140:141], v[0:1]
	v_mov_b64_e32 v[142:143], v[0:1]
	v_mov_b64_e32 v[144:145], v[0:1]
	v_mov_b64_e32 v[154:155], v[0:1]
	v_mov_b64_e32 v[156:157], v[0:1]
	v_mov_b64_e32 v[158:159], v[0:1]
	v_mov_b64_e32 v[160:161], v[0:1]
	s_barrier
